# s10 + na_bias_early: NA row body issues the 8 rel-pos-bias LDS reads of each q-block behind the K-fragment reads (before the two score MFMAs) instead of after them
# baseline (speedup 1.0000x reference)
.LBB0_307:
	s_add_i32 s16, s47, s49
	s_add_i32 s51, s16, -2
	s_cmp_ge_u32 s51, s24
	s_cselect_b64 s[16:17], -1, 0
	s_cmp_lt_u32 s51, s31
	s_cselect_b64 s[52:53], -1, 0
	s_and_b64 s[16:17], s[16:17], s[52:53]
	s_andn2_b64 vcc, exec, s[16:17]
	s_cbranch_vccnz .LBB0_309
	v_add_u32_e32 v85, v118, v107
	ds_read_b128 v[194:197], v85
	ds_read_b128 v[202:205], v85 offset:2048
	v_add_u32_e32 v193, v118, v108
	ds_read_b128 v[198:201], v193
	ds_read_b128 v[206:209], v193 offset:2048
	ds_read_b32 v236, v192
	ds_read_b32 v237, v191
	ds_read_b32 v238, v190
	ds_read_b32 v210, v189
	ds_read_b32 v211, v188
	ds_read_b32 v85, v187
	ds_read_b32 v212, v186
	ds_read_b32 v193, v185
	s_waitcnt lgkmcnt(11)
	v_mfma_f32_16x16x32_bf16 v[194:197], v[194:197], v[20:23], 0
	s_waitcnt lgkmcnt(9)
	v_mfma_f32_16x16x32_bf16 v[194:197], v[198:201], v[24:27], v[194:197]
	s_nop 7
	s_waitcnt lgkmcnt(7)
	v_add_f32_e32 v194, v194, v236
	v_exp_f32_e32 v214, v194
	s_waitcnt lgkmcnt(6)
	v_add_f32_e32 v194, v195, v237
	v_exp_f32_e32 v222, v194
	s_waitcnt lgkmcnt(5)
	v_add_f32_e32 v194, v196, v238
	v_mfma_f32_16x16x32_bf16 v[198:201], v[202:205], v[20:23], 0
	v_exp_f32_e32 v224, v194
	s_waitcnt lgkmcnt(4)
	v_add_f32_e32 v194, v197, v210
	v_exp_f32_e32 v226, v194
	v_mfma_f32_16x16x32_bf16 v[194:197], v[206:209], v[24:27], v[198:201]
	v_add_u32_e32 v215, 0, v178
	s_nop 1
	v_cvt_pk_bf16_f32 v198, v214, v222
	v_cvt_pk_bf16_f32 v199, v224, v226
	s_waitcnt lgkmcnt(2)
	s_nop 1
	v_add_f32_e32 v85, v195, v85
	v_exp_f32_e32 v230, v85
	s_waitcnt lgkmcnt(1)
	v_add_f32_e32 v85, v196, v212
	v_add_f32_e32 v194, v194, v211
	v_exp_f32_e32 v232, v85
	s_waitcnt lgkmcnt(0)
	v_add_f32_e32 v85, v197, v193
	v_add_u32_e32 v193, v119, v111
	v_exp_f32_e32 v228, v194
	ds_read_b64_tr_b16 v[194:195], v193 offset:8192
	ds_read_b64_tr_b16 v[196:197], v193 offset:10240
	v_exp_f32_e32 v234, v85
	v_add_u32_e32 v85, v119, v112
	v_cvt_pk_bf16_f32 v200, v228, v230
	ds_read_b64_tr_b16 v[202:203], v85 offset:8192
	ds_read_b64_tr_b16 v[204:205], v85 offset:10240
	v_cvt_pk_bf16_f32 v201, v232, v234
	v_add_u32_e32 v85, v119, v113
	v_add_u32_e32 v193, v120, v108
	s_waitcnt lgkmcnt(2)
	v_mfma_f32_16x16x32_bf16 v[76:79], v[194:197], v[198:201], v[76:79]
	ds_read_b64_tr_b16 v[194:195], v85 offset:8192
	ds_read_b64_tr_b16 v[196:197], v85 offset:10240
	v_add_u32_e32 v85, v119, v114
	s_waitcnt lgkmcnt(2)
	v_mfma_f32_16x16x32_bf16 v[64:67], v[202:205], v[198:201], v[64:67]
	ds_read_b64_tr_b16 v[202:203], v85 offset:8192
	ds_read_b64_tr_b16 v[204:205], v85 offset:10240
	v_add_u32_e32 v85, v120, v107
	ds_read_b128 v[206:209], v85 offset:2048
	s_waitcnt lgkmcnt(3)
	v_mfma_f32_16x16x32_bf16 v[72:75], v[194:197], v[198:201], v[72:75]
	ds_read_b128 v[194:197], v85
	ds_read_b128 v[210:213], v193
	ds_read_b128 v[218:221], v193 offset:2048
	ds_read_b32 v85, v184
	ds_read_b32 v193, v183
	ds_read_b32 v239, v182
	ds_read_b32 v240, v181
	ds_read_b32 v241, v180
	ds_read_b32 v242, v179
	ds_read_b32 v233, v215
	ds_read_b32 v217, v177
	s_waitcnt lgkmcnt(10)
	v_mfma_f32_16x16x32_bf16 v[194:197], v[194:197], v[36:39], 0
	s_waitcnt lgkmcnt(9)
	v_mfma_f32_16x16x32_bf16 v[194:197], v[210:213], v[40:43], v[194:197]
	s_nop 7
	s_waitcnt lgkmcnt(7)
	v_add_f32_e32 v85, v194, v85
	v_exp_f32_e32 v215, v85
	s_waitcnt lgkmcnt(6)
	v_add_f32_e32 v85, v195, v193
	v_exp_f32_e32 v223, v85
	v_mfma_f32_16x16x32_bf16 v[68:71], v[202:205], v[198:201], v[68:71]
	v_add_f32_e64 v194, v214, 0
	v_add_f32_e64 v195, v215, 0
	s_waitcnt lgkmcnt(5)
	v_add_f32_e32 v85, v196, v239
	v_pk_add_f32 v[202:203], v[194:195], v[222:223]
	v_mfma_f32_16x16x32_bf16 v[198:201], v[206:209], v[36:39], 0
	v_exp_f32_e32 v225, v85
	s_waitcnt lgkmcnt(4)
	v_add_f32_e32 v85, v197, v240
	v_exp_f32_e32 v227, v85
	v_mfma_f32_16x16x32_bf16 v[194:197], v[218:221], v[40:43], v[198:201]
	v_add_f32_e64 v210, v202, v224
	v_add_f32_e64 v211, v203, v225
	s_waitcnt lgkmcnt(3)
	s_nop 4
	v_add_f32_e32 v85, v194, v241
	v_exp_f32_e32 v229, v85
	s_waitcnt lgkmcnt(2)
	v_add_f32_e32 v85, v195, v242
	v_exp_f32_e32 v231, v85
	s_waitcnt lgkmcnt(1)
	v_add_f32_e32 v85, v196, v233
	v_exp_f32_e32 v233, v85
	s_waitcnt lgkmcnt(0)
	v_add_f32_e32 v85, v197, v217
	v_exp_f32_e32 v235, v85
	v_add_u32_e32 v85, v121, v111
	ds_read_b64_tr_b16 v[198:199], v85 offset:8192
	ds_read_b64_tr_b16 v[200:201], v85 offset:10240
	v_add_u32_e32 v85, v121, v112
	ds_read_b64_tr_b16 v[202:203], v85 offset:8192
	ds_read_b64_tr_b16 v[204:205], v85 offset:10240
	v_add_u32_e32 v85, v121, v113
	v_cvt_pk_bf16_f32 v194, v215, v223
	v_cvt_pk_bf16_f32 v195, v225, v227
	v_cvt_pk_bf16_f32 v196, v229, v231
	v_cvt_pk_bf16_f32 v197, v233, v235
	ds_read_b64_tr_b16 v[206:207], v85 offset:8192
	ds_read_b64_tr_b16 v[208:209], v85 offset:10240
	v_add_u32_e32 v85, v121, v114
	s_waitcnt lgkmcnt(4)
	v_mfma_f32_16x16x32_bf16 v[60:63], v[198:201], v[194:197], v[60:63]
	ds_read_b64_tr_b16 v[198:199], v85 offset:8192
	ds_read_b64_tr_b16 v[200:201], v85 offset:10240
	s_waitcnt lgkmcnt(4)
	v_mfma_f32_16x16x32_bf16 v[56:59], v[202:205], v[194:197], v[56:59]
	v_add_f32_e64 v202, v210, v226
	v_add_f32_e64 v203, v211, v227
	v_pk_add_f32 v[202:203], v[202:203], v[228:229]
	s_waitcnt lgkmcnt(2)
	v_mfma_f32_16x16x32_bf16 v[52:55], v[206:209], v[194:197], v[52:55]
	v_add_f32_e64 v202, v202, v230
	v_add_f32_e64 v203, v203, v231
	v_pk_add_f32 v[202:203], v[202:203], v[232:233]
	s_waitcnt lgkmcnt(0)
	v_mfma_f32_16x16x32_bf16 v[44:47], v[198:201], v[194:197], v[44:47]
	v_add_f32_e64 v202, v202, v234
	v_add_f32_e64 v203, v203, v235
	v_pk_add_f32 v[102:103], v[202:203], v[102:103]

.LBB0_314:
	s_add_i32 s16, s47, s49
	s_add_i32 s51, s16, -1
	s_cmp_ge_u32 s51, s24
	s_cselect_b64 s[16:17], -1, 0
	s_cmp_lt_u32 s51, s31
	s_cselect_b64 s[52:53], -1, 0
	s_and_b64 s[16:17], s[16:17], s[52:53]
	s_andn2_b64 vcc, exec, s[16:17]
	s_cbranch_vccnz .LBB0_316
	v_add_u32_e32 v85, v118, v107
	ds_read_b128 v[194:197], v85 offset:32768
	ds_read_b128 v[202:205], v85 offset:34816
	v_add_u32_e32 v193, v118, v108
	ds_read_b128 v[198:201], v193 offset:32768
	ds_read_b128 v[206:209], v193 offset:34816
	v_add_u32_e32 v210, s48, v176
	v_add_u32_e32 v211, s48, v175
	v_add_u32_e32 v213, s48, v173
	v_add_u32_e32 v85, s48, v171
	v_add_u32_e32 v215, s48, v170
	v_add_u32_e32 v193, s48, v169
	v_add_u32_e32 v212, s48, v174
	v_add_u32_e32 v214, s48, v172
	ds_read_b32 v236, v210
	ds_read_b32 v237, v211
	ds_read_b32 v238, v212
	ds_read_b32 v211, v213
	ds_read_b32 v213, v214
	ds_read_b32 v85, v85
	ds_read_b32 v215, v215
	ds_read_b32 v193, v193
	s_waitcnt lgkmcnt(11)
	v_mfma_f32_16x16x32_bf16 v[194:197], v[194:197], v[20:23], 0
	s_waitcnt lgkmcnt(9)
	v_mfma_f32_16x16x32_bf16 v[194:197], v[198:201], v[24:27], v[194:197]
	s_nop 7
	s_waitcnt lgkmcnt(7)
	v_add_f32_e32 v194, v194, v236
	v_exp_f32_e32 v210, v194
	s_waitcnt lgkmcnt(6)
	v_add_f32_e32 v194, v195, v237
	v_exp_f32_e32 v212, v194
	s_waitcnt lgkmcnt(5)
	v_add_f32_e32 v194, v196, v238
	v_mfma_f32_16x16x32_bf16 v[198:201], v[202:205], v[20:23], 0
	v_exp_f32_e32 v214, v194
	s_waitcnt lgkmcnt(4)
	v_add_f32_e32 v194, v197, v211
	v_exp_f32_e32 v218, v194
	v_mfma_f32_16x16x32_bf16 v[194:197], v[206:209], v[24:27], v[198:201]
	v_cvt_pk_bf16_f32 v202, v210, v212
	v_add_u32_e32 v211, s48, v162
	v_cvt_pk_bf16_f32 v203, v214, v218
	s_waitcnt lgkmcnt(2)
	s_nop 3
	v_add_f32_e32 v85, v195, v85
	v_exp_f32_e32 v222, v85
	s_waitcnt lgkmcnt(1)
	v_add_f32_e32 v85, v196, v215
	v_add_f32_e32 v194, v194, v213
	v_exp_f32_e32 v224, v85
	s_waitcnt lgkmcnt(0)
	v_add_f32_e32 v85, v197, v193
	v_add_u32_e32 v193, v119, v111
	v_exp_f32_e32 v220, v194
	ds_read_b64_tr_b16 v[194:195], v193 offset:40960
	ds_read_b64_tr_b16 v[196:197], v193 offset:43008
	v_exp_f32_e32 v226, v85
	v_add_u32_e32 v85, v119, v112
	ds_read_b64_tr_b16 v[198:199], v85 offset:40960
	ds_read_b64_tr_b16 v[200:201], v85 offset:43008
	v_cvt_pk_bf16_f32 v204, v220, v222
	v_cvt_pk_bf16_f32 v205, v224, v226
	v_add_u32_e32 v85, v119, v113
	v_add_u32_e32 v193, v120, v108
	s_waitcnt lgkmcnt(2)
	v_mfma_f32_16x16x32_bf16 v[76:79], v[194:197], v[202:205], v[76:79]
	ds_read_b64_tr_b16 v[194:195], v85 offset:40960
	ds_read_b64_tr_b16 v[196:197], v85 offset:43008
	v_add_u32_e32 v85, v119, v114
	v_add_u32_e32 v213, s48, v161
	s_waitcnt lgkmcnt(2)
	v_mfma_f32_16x16x32_bf16 v[64:67], v[198:201], v[202:205], v[64:67]
	ds_read_b64_tr_b16 v[198:199], v85 offset:40960
	ds_read_b64_tr_b16 v[200:201], v85 offset:43008
	v_add_u32_e32 v85, v120, v107
	s_waitcnt lgkmcnt(2)
	v_mfma_f32_16x16x32_bf16 v[72:75], v[194:197], v[202:205], v[72:75]
	ds_read_b128 v[194:197], v85 offset:32768
	s_waitcnt lgkmcnt(1)
	v_mfma_f32_16x16x32_bf16 v[68:71], v[198:201], v[202:205], v[68:71]
	ds_read_b128 v[198:201], v85 offset:34816
	ds_read_b128 v[202:205], v193 offset:32768
	ds_read_b128 v[206:209], v193 offset:34816
	v_add_u32_e32 v85, s48, v168
	v_add_u32_e32 v193, s48, v167
	v_add_u32_e32 v243, s48, v166
	v_add_u32_e32 v244, s48, v165
	v_add_u32_e32 v245, s48, v164
	v_add_u32_e32 v246, s48, v163
	ds_read_b32 v85, v85
	ds_read_b32 v193, v193
	ds_read_b32 v243, v243
	ds_read_b32 v244, v244
	ds_read_b32 v245, v245
	ds_read_b32 v246, v246
	ds_read_b32 v217, v211
	ds_read_b32 v227, v213
	s_waitcnt lgkmcnt(11)
	v_mfma_f32_16x16x32_bf16 v[194:197], v[194:197], v[36:39], 0
	s_waitcnt lgkmcnt(9)
	v_mfma_f32_16x16x32_bf16 v[194:197], v[202:205], v[40:43], v[194:197]
	v_mfma_f32_16x16x32_bf16 v[198:201], v[198:201], v[36:39], 0
	s_nop 7
	s_waitcnt lgkmcnt(7)
	v_add_f32_e32 v85, v194, v85
	v_exp_f32_e32 v211, v85
	s_waitcnt lgkmcnt(6)
	v_add_f32_e32 v85, v195, v193
	v_exp_f32_e32 v213, v85
	s_waitcnt lgkmcnt(5)
	v_add_f32_e32 v85, v196, v243
	v_exp_f32_e32 v215, v85
	s_waitcnt lgkmcnt(4)
	v_add_f32_e32 v85, v197, v244
	v_mfma_f32_16x16x32_bf16 v[194:197], v[206:209], v[40:43], v[198:201]
	v_exp_f32_e32 v219, v85
	s_waitcnt lgkmcnt(3)
	s_nop 5
	v_add_f32_e32 v85, v194, v245
	v_exp_f32_e32 v221, v85
	s_waitcnt lgkmcnt(2)
	v_add_f32_e32 v85, v195, v246
	v_exp_f32_e32 v223, v85
	s_waitcnt lgkmcnt(1)
	v_add_f32_e32 v85, v196, v217
	v_exp_f32_e32 v225, v85
	s_waitcnt lgkmcnt(0)
	v_add_f32_e32 v85, v197, v227
	v_exp_f32_e32 v227, v85
	v_add_u32_e32 v85, v121, v111
	ds_read_b64_tr_b16 v[198:199], v85 offset:40960
	ds_read_b64_tr_b16 v[200:201], v85 offset:43008
	v_pk_add_f32 v[194:195], v[210:211], 0 op_sel_hi:[1,0]
	v_add_u32_e32 v85, v121, v112
	v_pk_add_f32 v[194:195], v[194:195], v[212:213]
	ds_read_b64_tr_b16 v[202:203], v85 offset:40960
	ds_read_b64_tr_b16 v[204:205], v85 offset:43008
	v_add_u32_e32 v85, v121, v113
	v_pk_add_f32 v[228:229], v[194:195], v[214:215]
	v_cvt_pk_bf16_f32 v194, v211, v213
	v_cvt_pk_bf16_f32 v195, v215, v219
	v_cvt_pk_bf16_f32 v196, v221, v223
	v_cvt_pk_bf16_f32 v197, v225, v227
	ds_read_b64_tr_b16 v[206:207], v85 offset:40960
	ds_read_b64_tr_b16 v[208:209], v85 offset:43008
	v_add_u32_e32 v85, v121, v114
	s_waitcnt lgkmcnt(4)
	v_mfma_f32_16x16x32_bf16 v[60:63], v[198:201], v[194:197], v[60:63]
	ds_read_b64_tr_b16 v[198:199], v85 offset:40960
	ds_read_b64_tr_b16 v[200:201], v85 offset:43008
	s_waitcnt lgkmcnt(4)
	v_mfma_f32_16x16x32_bf16 v[56:59], v[202:205], v[194:197], v[56:59]
	v_add_f32_e64 v202, v228, v218
	v_add_f32_e64 v203, v229, v219
	v_pk_add_f32 v[202:203], v[202:203], v[220:221]
	s_waitcnt lgkmcnt(2)
	v_mfma_f32_16x16x32_bf16 v[52:55], v[206:209], v[194:197], v[52:55]
	v_add_f32_e64 v202, v202, v222
	v_add_f32_e64 v203, v203, v223
	v_pk_add_f32 v[202:203], v[202:203], v[224:225]
	s_waitcnt lgkmcnt(0)
	v_mfma_f32_16x16x32_bf16 v[44:47], v[198:201], v[194:197], v[44:47]
	v_add_f32_e64 v202, v202, v226
	v_add_f32_e64 v203, v203, v227
	v_pk_add_f32 v[102:103], v[202:203], v[102:103]
